# K-loop LDS-DMA addressing in SGPR-base + 32-bit VGPR offset form (64-bit VALU address adds removed); rest as v086
# speedup vs baseline: 1.0054x; 1.0054x over previous
.LBB0_131:
	ds_read_b128 v[146:149], v157
	ds_read_b128 v[150:153], v157 offset:1024
	ds_read_b128 v[160:163], v157 offset:2048
	ds_read_b128 v[164:167], v157 offset:3072
	ds_read_b128 v[168:171], v158
	ds_read_b128 v[172:175], v158 offset:1024
	ds_read_b128 v[176:179], v158 offset:2048
	ds_read_b128 v[180:183], v158 offset:3072
	s_add_u32 s34, s30, 0xfff80080
	s_addc_u32 s35, s31, -1
	s_cmp_eq_u32 s55, 28
	s_cselect_b32 s37, s23, s35
	s_cselect_b32 s36, s51, s34
	s_cselect_b32 s35, s21, s54
	s_cselect_b32 s34, s52, s53
	s_add_u32 s100, s36, 0x80
	s_addc_u32 s101, s37, 0
	s_add_i32 m0, s29, 0xc000
	ds_read_b128 v[184:187], v159
	ds_read_b128 v[188:191], v159 offset:1024
	ds_read_b128 v[192:195], v159 offset:2048
	ds_read_b128 v[196:199], v159 offset:3072
	ds_read_b128 v[200:203], v159 offset:4096
	ds_read_b128 v[204:207], v159 offset:5120
	ds_read_b128 v[208:211], v159 offset:6144
	ds_read_b128 v[212:215], v159 offset:7168
	global_load_lds_dwordx4 v138, s[30:31]
	s_add_i32 m0, s29, 0xe000
	s_nop 0
	global_load_lds_dwordx4 v140, s[30:31]
	s_waitcnt vmcnt(8)
	s_waitcnt lgkmcnt(0)
	s_barrier
	s_waitcnt lgkmcnt(0)
	v_mfma_f32_16x16x32_bf16 v[124:127], v[146:149], v[184:187], v[124:127]
	v_mfma_f32_16x16x32_bf16 v[124:127], v[150:153], v[188:191], v[124:127]
	v_mfma_f32_16x16x32_bf16 v[120:123], v[160:163], v[184:187], v[120:123]
	v_mfma_f32_16x16x32_bf16 v[120:123], v[164:167], v[188:191], v[120:123]
	v_mfma_f32_16x16x32_bf16 v[104:107], v[160:163], v[192:195], v[104:107]
	v_mfma_f32_16x16x32_bf16 v[104:107], v[164:167], v[196:199], v[104:107]
	v_mfma_f32_16x16x32_bf16 v[108:111], v[146:149], v[192:195], v[108:111]
	v_mfma_f32_16x16x32_bf16 v[108:111], v[150:153], v[196:199], v[108:111]
	v_mfma_f32_16x16x32_bf16 v[92:95], v[146:149], v[200:203], v[92:95]
	v_mfma_f32_16x16x32_bf16 v[92:95], v[150:153], v[204:207], v[92:95]
	v_mfma_f32_16x16x32_bf16 v[88:91], v[160:163], v[200:203], v[88:91]
	v_mfma_f32_16x16x32_bf16 v[88:91], v[164:167], v[204:207], v[88:91]
	v_mfma_f32_16x16x32_bf16 v[72:75], v[160:163], v[208:211], v[72:75]
	v_mfma_f32_16x16x32_bf16 v[72:75], v[164:167], v[212:215], v[72:75]
	v_mfma_f32_16x16x32_bf16 v[76:79], v[146:149], v[208:211], v[76:79]
	v_mfma_f32_16x16x32_bf16 v[76:79], v[150:153], v[212:215], v[76:79]
	v_mfma_f32_16x16x32_bf16 v[116:119], v[168:171], v[184:187], v[116:119]
	v_mfma_f32_16x16x32_bf16 v[116:119], v[172:175], v[188:191], v[116:119]
	v_mfma_f32_16x16x32_bf16 v[112:115], v[176:179], v[184:187], v[112:115]
	v_mfma_f32_16x16x32_bf16 v[112:115], v[180:183], v[188:191], v[112:115]
	v_mfma_f32_16x16x32_bf16 v[96:99], v[176:179], v[192:195], v[96:99]
	v_mfma_f32_16x16x32_bf16 v[96:99], v[180:183], v[196:199], v[96:99]
	v_mfma_f32_16x16x32_bf16 v[100:103], v[168:171], v[192:195], v[100:103]
	v_mfma_f32_16x16x32_bf16 v[100:103], v[172:175], v[196:199], v[100:103]
	v_mfma_f32_16x16x32_bf16 v[84:87], v[168:171], v[200:203], v[84:87]
	v_mfma_f32_16x16x32_bf16 v[84:87], v[172:175], v[204:207], v[84:87]
	v_mfma_f32_16x16x32_bf16 v[80:83], v[176:179], v[200:203], v[80:83]
	v_mfma_f32_16x16x32_bf16 v[80:83], v[180:183], v[204:207], v[80:83]
	v_mfma_f32_16x16x32_bf16 v[64:67], v[176:179], v[208:211], v[64:67]
	v_mfma_f32_16x16x32_bf16 v[64:67], v[180:183], v[212:215], v[64:67]
	v_mfma_f32_16x16x32_bf16 v[68:71], v[168:171], v[208:211], v[68:71]
	v_mfma_f32_16x16x32_bf16 v[68:71], v[172:175], v[212:215], v[68:71]
	s_barrier
	s_add_i32 s56, s47, s33
	s_mov_b32 m0, s56
	ds_read_b128 v[184:187], v159 offset:16384
	ds_read_b128 v[188:191], v159 offset:17408
	ds_read_b128 v[192:195], v159 offset:18432
	ds_read_b128 v[196:199], v159 offset:19456
	ds_read_b128 v[200:203], v159 offset:20480
	ds_read_b128 v[204:207], v159 offset:21504
	ds_read_b128 v[208:211], v159 offset:22528
	ds_read_b128 v[212:215], v159 offset:23552
	global_load_lds_dwordx4 v134, s[34:35]
	s_add_i32 m0, s56, 0x2000
	s_add_u32 s56, s34, 0x80000
	s_addc_u32 s57, s35, 0
	s_add_i32 s58, s48, s33
	global_load_lds_dwordx4 v130, s[34:35]
	s_mov_b32 m0, s58
	s_nop 0
	global_load_lds_dwordx4 v134, s[56:57]
	s_add_i32 m0, s58, 0x2000
	s_nop 0
	global_load_lds_dwordx4 v130, s[56:57]
	s_mov_b32 m0, s29
	s_nop 0
	global_load_lds_dwordx4 v136, s[36:37]
	s_mov_b32 m0, s40
	s_nop 0
	global_load_lds_dwordx4 v132, s[36:37]
	s_waitcnt vmcnt(8)
	s_waitcnt lgkmcnt(0)
	s_barrier
	s_waitcnt lgkmcnt(0)
	v_mfma_f32_16x16x32_bf16 v[60:63], v[146:149], v[184:187], v[60:63]
	v_mfma_f32_16x16x32_bf16 v[60:63], v[150:153], v[188:191], v[60:63]
	v_mfma_f32_16x16x32_bf16 v[56:59], v[160:163], v[184:187], v[56:59]
	v_mfma_f32_16x16x32_bf16 v[56:59], v[164:167], v[188:191], v[56:59]
	v_mfma_f32_16x16x32_bf16 v[40:43], v[160:163], v[192:195], v[40:43]
	v_mfma_f32_16x16x32_bf16 v[40:43], v[164:167], v[196:199], v[40:43]
	v_mfma_f32_16x16x32_bf16 v[44:47], v[146:149], v[192:195], v[44:47]
	v_mfma_f32_16x16x32_bf16 v[44:47], v[150:153], v[196:199], v[44:47]
	v_mfma_f32_16x16x32_bf16 v[28:31], v[146:149], v[200:203], v[28:31]
	v_mfma_f32_16x16x32_bf16 v[28:31], v[150:153], v[204:207], v[28:31]
	v_mfma_f32_16x16x32_bf16 v[24:27], v[160:163], v[200:203], v[24:27]
	v_mfma_f32_16x16x32_bf16 v[24:27], v[164:167], v[204:207], v[24:27]
	v_mfma_f32_16x16x32_bf16 v[8:11], v[160:163], v[208:211], v[8:11]
	v_mfma_f32_16x16x32_bf16 v[8:11], v[164:167], v[212:215], v[8:11]
	v_mfma_f32_16x16x32_bf16 v[12:15], v[146:149], v[208:211], v[12:15]
	v_mfma_f32_16x16x32_bf16 v[12:15], v[150:153], v[212:215], v[12:15]
	v_mfma_f32_16x16x32_bf16 v[52:55], v[168:171], v[184:187], v[52:55]
	v_mfma_f32_16x16x32_bf16 v[52:55], v[172:175], v[188:191], v[52:55]
	v_mfma_f32_16x16x32_bf16 v[48:51], v[176:179], v[184:187], v[48:51]
	v_mfma_f32_16x16x32_bf16 v[48:51], v[180:183], v[188:191], v[48:51]
	v_mfma_f32_16x16x32_bf16 v[32:35], v[176:179], v[192:195], v[32:35]
	v_mfma_f32_16x16x32_bf16 v[32:35], v[180:183], v[196:199], v[32:35]
	v_mfma_f32_16x16x32_bf16 v[36:39], v[168:171], v[192:195], v[36:39]
	v_mfma_f32_16x16x32_bf16 v[36:39], v[172:175], v[196:199], v[36:39]
	v_mfma_f32_16x16x32_bf16 v[20:23], v[168:171], v[200:203], v[20:23]
	v_mfma_f32_16x16x32_bf16 v[20:23], v[172:175], v[204:207], v[20:23]
	v_mfma_f32_16x16x32_bf16 v[16:19], v[176:179], v[200:203], v[16:19]
	v_mfma_f32_16x16x32_bf16 v[16:19], v[180:183], v[204:207], v[16:19]
	v_mfma_f32_16x16x32_bf16 v[0:3], v[176:179], v[208:211], v[0:3]
	v_mfma_f32_16x16x32_bf16 v[0:3], v[180:183], v[212:215], v[0:3]
	v_mfma_f32_16x16x32_bf16 v[4:7], v[168:171], v[208:211], v[4:7]
	v_mfma_f32_16x16x32_bf16 v[4:7], v[172:175], v[212:215], v[4:7]
	s_barrier
	s_add_i32 s56, 0, 0x18000
	s_add_i32 s57, 0, 0x1c000
	v_add_u32_e32 v164, s56, v155
	v_add_u32_e32 v180, s57, v155
	ds_read_b128 v[146:149], v164
	ds_read_b128 v[150:153], v164 offset:1024
	ds_read_b128 v[160:163], v164 offset:2048
	ds_read_b128 v[164:167], v164 offset:3072
	ds_read_b128 v[168:171], v180
	ds_read_b128 v[172:175], v180 offset:1024
	ds_read_b128 v[176:179], v180 offset:2048
	ds_read_b128 v[180:183], v180 offset:3072
	s_add_u32 s36, s36, 0x80000
	s_addc_u32 s37, s37, 0
	s_mov_b32 m0, s41
	ds_read_b128 v[184:187], v159 offset:32768
	ds_read_b128 v[188:191], v159 offset:33792
	ds_read_b128 v[192:195], v159 offset:34816
	ds_read_b128 v[196:199], v159 offset:35840
	ds_read_b128 v[200:203], v159 offset:36864
	ds_read_b128 v[204:207], v159 offset:37888
	ds_read_b128 v[208:211], v159 offset:38912
	ds_read_b128 v[212:215], v159 offset:39936
	global_load_lds_dwordx4 v136, s[36:37]
	s_mov_b32 m0, s42
	s_nop 0
	global_load_lds_dwordx4 v132, s[36:37]
	s_waitcnt vmcnt(8)
	s_waitcnt lgkmcnt(0)
	s_barrier
	s_waitcnt lgkmcnt(0)
	v_mfma_f32_16x16x32_bf16 v[124:127], v[146:149], v[184:187], v[124:127]
	v_mfma_f32_16x16x32_bf16 v[124:127], v[150:153], v[188:191], v[124:127]
	v_mfma_f32_16x16x32_bf16 v[120:123], v[160:163], v[184:187], v[120:123]
	v_mfma_f32_16x16x32_bf16 v[120:123], v[164:167], v[188:191], v[120:123]
	v_mfma_f32_16x16x32_bf16 v[104:107], v[160:163], v[192:195], v[104:107]
	v_mfma_f32_16x16x32_bf16 v[104:107], v[164:167], v[196:199], v[104:107]
	v_mfma_f32_16x16x32_bf16 v[108:111], v[146:149], v[192:195], v[108:111]
	v_mfma_f32_16x16x32_bf16 v[108:111], v[150:153], v[196:199], v[108:111]
	v_mfma_f32_16x16x32_bf16 v[92:95], v[146:149], v[200:203], v[92:95]
	v_mfma_f32_16x16x32_bf16 v[92:95], v[150:153], v[204:207], v[92:95]
	v_mfma_f32_16x16x32_bf16 v[88:91], v[160:163], v[200:203], v[88:91]
	v_mfma_f32_16x16x32_bf16 v[88:91], v[164:167], v[204:207], v[88:91]
	v_mfma_f32_16x16x32_bf16 v[72:75], v[160:163], v[208:211], v[72:75]
	v_mfma_f32_16x16x32_bf16 v[72:75], v[164:167], v[212:215], v[72:75]
	v_mfma_f32_16x16x32_bf16 v[76:79], v[146:149], v[208:211], v[76:79]
	v_mfma_f32_16x16x32_bf16 v[76:79], v[150:153], v[212:215], v[76:79]
	v_mfma_f32_16x16x32_bf16 v[116:119], v[168:171], v[184:187], v[116:119]
	v_mfma_f32_16x16x32_bf16 v[116:119], v[172:175], v[188:191], v[116:119]
	v_mfma_f32_16x16x32_bf16 v[112:115], v[176:179], v[184:187], v[112:115]
	v_mfma_f32_16x16x32_bf16 v[112:115], v[180:183], v[188:191], v[112:115]
	v_mfma_f32_16x16x32_bf16 v[96:99], v[176:179], v[192:195], v[96:99]
	v_mfma_f32_16x16x32_bf16 v[96:99], v[180:183], v[196:199], v[96:99]
	v_mfma_f32_16x16x32_bf16 v[100:103], v[168:171], v[192:195], v[100:103]
	v_mfma_f32_16x16x32_bf16 v[100:103], v[172:175], v[196:199], v[100:103]
	v_mfma_f32_16x16x32_bf16 v[84:87], v[168:171], v[200:203], v[84:87]
	v_mfma_f32_16x16x32_bf16 v[84:87], v[172:175], v[204:207], v[84:87]
	v_mfma_f32_16x16x32_bf16 v[80:83], v[176:179], v[200:203], v[80:83]
	v_mfma_f32_16x16x32_bf16 v[80:83], v[180:183], v[204:207], v[80:83]
	v_mfma_f32_16x16x32_bf16 v[64:67], v[176:179], v[208:211], v[64:67]
	v_mfma_f32_16x16x32_bf16 v[64:67], v[180:183], v[212:215], v[64:67]
	v_mfma_f32_16x16x32_bf16 v[68:71], v[168:171], v[208:211], v[68:71]
	v_mfma_f32_16x16x32_bf16 v[68:71], v[172:175], v[212:215], v[68:71]
	s_barrier
	s_add_i32 s36, s56, s33
	s_add_u32 s98, s34, 0x80
	s_addc_u32 s99, s35, 0
	s_mov_b32 m0, s36
	ds_read_b128 v[184:187], v159 offset:49152
	ds_read_b128 v[188:191], v159 offset:50176
	ds_read_b128 v[192:195], v159 offset:51200
	ds_read_b128 v[196:199], v159 offset:52224
	ds_read_b128 v[200:203], v159 offset:53248
	ds_read_b128 v[204:207], v159 offset:54272
	ds_read_b128 v[208:211], v159 offset:55296
	ds_read_b128 v[212:215], v159 offset:56320
	global_load_lds_dwordx4 v134, s[98:99]
	s_add_i32 m0, s36, 0x2000
	s_add_u32 s34, s34, 0x80080
	s_addc_u32 s35, s35, 0
	s_add_i32 s36, s57, s33
	global_load_lds_dwordx4 v130, s[98:99]
	s_mov_b32 m0, s36
	s_nop 0
	global_load_lds_dwordx4 v134, s[34:35]
	s_add_i32 m0, s36, 0x2000
	s_nop 0
	global_load_lds_dwordx4 v130, s[34:35]
	s_mov_b32 m0, s44
	s_nop 0
	global_load_lds_dwordx4 v136, s[100:101]
	s_mov_b32 m0, s45
	s_nop 0
	global_load_lds_dwordx4 v132, s[100:101]
	s_waitcnt vmcnt(8)
	s_waitcnt lgkmcnt(0)
	s_barrier
	s_waitcnt lgkmcnt(0)
	v_mfma_f32_16x16x32_bf16 v[60:63], v[146:149], v[184:187], v[60:63]
	v_mfma_f32_16x16x32_bf16 v[60:63], v[150:153], v[188:191], v[60:63]
	v_mfma_f32_16x16x32_bf16 v[56:59], v[160:163], v[184:187], v[56:59]
	v_mfma_f32_16x16x32_bf16 v[56:59], v[164:167], v[188:191], v[56:59]
	v_mfma_f32_16x16x32_bf16 v[40:43], v[160:163], v[192:195], v[40:43]
	v_mfma_f32_16x16x32_bf16 v[40:43], v[164:167], v[196:199], v[40:43]
	v_mfma_f32_16x16x32_bf16 v[44:47], v[146:149], v[192:195], v[44:47]
	v_mfma_f32_16x16x32_bf16 v[44:47], v[150:153], v[196:199], v[44:47]
	v_mfma_f32_16x16x32_bf16 v[28:31], v[146:149], v[200:203], v[28:31]
	v_mfma_f32_16x16x32_bf16 v[28:31], v[150:153], v[204:207], v[28:31]
	v_mfma_f32_16x16x32_bf16 v[24:27], v[160:163], v[200:203], v[24:27]
	v_mfma_f32_16x16x32_bf16 v[24:27], v[164:167], v[204:207], v[24:27]
	v_mfma_f32_16x16x32_bf16 v[8:11], v[160:163], v[208:211], v[8:11]
	v_mfma_f32_16x16x32_bf16 v[8:11], v[164:167], v[212:215], v[8:11]
	v_mfma_f32_16x16x32_bf16 v[12:15], v[146:149], v[208:211], v[12:15]
	v_mfma_f32_16x16x32_bf16 v[12:15], v[150:153], v[212:215], v[12:15]
	v_mfma_f32_16x16x32_bf16 v[52:55], v[168:171], v[184:187], v[52:55]
	v_mfma_f32_16x16x32_bf16 v[52:55], v[172:175], v[188:191], v[52:55]
	v_mfma_f32_16x16x32_bf16 v[48:51], v[176:179], v[184:187], v[48:51]
	v_mfma_f32_16x16x32_bf16 v[48:51], v[180:183], v[188:191], v[48:51]
	v_mfma_f32_16x16x32_bf16 v[32:35], v[176:179], v[192:195], v[32:35]
	v_mfma_f32_16x16x32_bf16 v[32:35], v[180:183], v[196:199], v[32:35]
	v_mfma_f32_16x16x32_bf16 v[36:39], v[168:171], v[192:195], v[36:39]
	v_mfma_f32_16x16x32_bf16 v[36:39], v[172:175], v[196:199], v[36:39]
	v_mfma_f32_16x16x32_bf16 v[20:23], v[168:171], v[200:203], v[20:23]
	v_mfma_f32_16x16x32_bf16 v[20:23], v[172:175], v[204:207], v[20:23]
	v_mfma_f32_16x16x32_bf16 v[16:19], v[176:179], v[200:203], v[16:19]
	v_mfma_f32_16x16x32_bf16 v[16:19], v[180:183], v[204:207], v[16:19]
	v_mfma_f32_16x16x32_bf16 v[0:3], v[176:179], v[208:211], v[0:3]
	v_mfma_f32_16x16x32_bf16 v[0:3], v[180:183], v[212:215], v[0:3]
	v_mfma_f32_16x16x32_bf16 v[4:7], v[168:171], v[208:211], v[4:7]
	v_mfma_f32_16x16x32_bf16 v[4:7], v[172:175], v[212:215], v[4:7]
	s_barrier
	s_add_i32 s55, s55, 2
	s_add_u32 s30, s30, 0x100
	s_addc_u32 s31, s31, 0
	s_add_u32 s53, s53, 0x100
	s_addc_u32 s54, s54, 0
	s_cmp_gt_u32 s55, 29
	s_cbranch_scc0 .LBB0_131
	s_and_b64 vcc, exec, s[18:19]
	s_cbranch_vccz .LBB0_134
	s_barrier

.LBB0_585:
	v_add_u32_e32 v166, s42, v152
	v_add_u32_e32 v182, s43, v152
	s_add_u32 s26, s12, s24
	ds_read_b128 v[154:157], v166
	ds_read_b128 v[158:161], v166 offset:1024
	ds_read_b128 v[162:165], v166 offset:2048
	ds_read_b128 v[166:169], v166 offset:3072
	ds_read_b128 v[170:173], v182
	ds_read_b128 v[174:177], v182 offset:1024
	ds_read_b128 v[178:181], v182 offset:2048
	ds_read_b128 v[182:185], v182 offset:3072
	s_addc_u32 s27, s13, s25
	s_add_u32 s26, s26, 0x100
	s_addc_u32 s27, s27, 0
	s_add_u32 s50, s45, s24
	s_addc_u32 s51, s46, s25
	s_cmpk_eq_i32 s24, 0xf00
	s_cselect_b32 s29, s19, s27
	s_cselect_b32 s28, s47, s26
	s_cselect_b32 s27, s17, s51
	s_cselect_b32 s26, s48, s50
	s_add_u32 s100, s28, 0x80
	s_addc_u32 s101, s29, 0
	v_lshl_add_u64 v[218:219], v[146:147], 0, s[24:25]
	s_add_i32 m0, s11, 0xc000
	ds_read_b128 v[186:189], v153
	ds_read_b128 v[190:193], v153 offset:1024
	ds_read_b128 v[194:197], v153 offset:2048
	ds_read_b128 v[198:201], v153 offset:3072
	ds_read_b128 v[202:205], v153 offset:4096
	ds_read_b128 v[206:209], v153 offset:5120
	ds_read_b128 v[210:213], v153 offset:6144
	ds_read_b128 v[214:217], v153 offset:7168
	global_load_lds_dwordx4 v[218:219], off
	v_lshl_add_u64 v[218:219], v[148:149], 0, s[24:25]
	s_add_i32 m0, s11, 0xe000
	s_nop 0
	global_load_lds_dwordx4 v[218:219], off
	s_waitcnt vmcnt(8)
	s_waitcnt lgkmcnt(0)
	s_barrier
	s_waitcnt lgkmcnt(0)
	v_mfma_f32_16x16x32_bf16 v[124:127], v[154:157], v[186:189], v[124:127]
	v_mfma_f32_16x16x32_bf16 v[124:127], v[158:161], v[190:193], v[124:127]
	v_mfma_f32_16x16x32_bf16 v[120:123], v[162:165], v[186:189], v[120:123]
	v_mfma_f32_16x16x32_bf16 v[120:123], v[166:169], v[190:193], v[120:123]
	v_mfma_f32_16x16x32_bf16 v[104:107], v[162:165], v[194:197], v[104:107]
	v_mfma_f32_16x16x32_bf16 v[104:107], v[166:169], v[198:201], v[104:107]
	v_mfma_f32_16x16x32_bf16 v[108:111], v[154:157], v[194:197], v[108:111]
	v_mfma_f32_16x16x32_bf16 v[108:111], v[158:161], v[198:201], v[108:111]
	v_mfma_f32_16x16x32_bf16 v[92:95], v[154:157], v[202:205], v[92:95]
	v_mfma_f32_16x16x32_bf16 v[92:95], v[158:161], v[206:209], v[92:95]
	v_mfma_f32_16x16x32_bf16 v[88:91], v[162:165], v[202:205], v[88:91]
	v_mfma_f32_16x16x32_bf16 v[88:91], v[166:169], v[206:209], v[88:91]
	v_mfma_f32_16x16x32_bf16 v[72:75], v[162:165], v[210:213], v[72:75]
	v_mfma_f32_16x16x32_bf16 v[72:75], v[166:169], v[214:217], v[72:75]
	v_mfma_f32_16x16x32_bf16 v[76:79], v[154:157], v[210:213], v[76:79]
	v_mfma_f32_16x16x32_bf16 v[76:79], v[158:161], v[214:217], v[76:79]
	v_mfma_f32_16x16x32_bf16 v[116:119], v[170:173], v[186:189], v[116:119]
	v_mfma_f32_16x16x32_bf16 v[116:119], v[174:177], v[190:193], v[116:119]
	v_mfma_f32_16x16x32_bf16 v[112:115], v[178:181], v[186:189], v[112:115]
	v_mfma_f32_16x16x32_bf16 v[112:115], v[182:185], v[190:193], v[112:115]
	v_mfma_f32_16x16x32_bf16 v[96:99], v[178:181], v[194:197], v[96:99]
	v_mfma_f32_16x16x32_bf16 v[96:99], v[182:185], v[198:201], v[96:99]
	v_mfma_f32_16x16x32_bf16 v[100:103], v[170:173], v[194:197], v[100:103]
	v_mfma_f32_16x16x32_bf16 v[100:103], v[174:177], v[198:201], v[100:103]
	v_mfma_f32_16x16x32_bf16 v[84:87], v[170:173], v[202:205], v[84:87]
	v_mfma_f32_16x16x32_bf16 v[84:87], v[174:177], v[206:209], v[84:87]
	v_mfma_f32_16x16x32_bf16 v[80:83], v[178:181], v[202:205], v[80:83]
	v_mfma_f32_16x16x32_bf16 v[80:83], v[182:185], v[206:209], v[80:83]
	v_mfma_f32_16x16x32_bf16 v[64:67], v[178:181], v[210:213], v[64:67]
	v_mfma_f32_16x16x32_bf16 v[64:67], v[182:185], v[214:217], v[64:67]
	v_mfma_f32_16x16x32_bf16 v[68:71], v[170:173], v[210:213], v[68:71]
	v_mfma_f32_16x16x32_bf16 v[68:71], v[174:177], v[214:217], v[68:71]
	s_barrier
	s_add_i32 s50, s42, s35
	s_mov_b32 m0, s50
	ds_read_b128 v[186:189], v153 offset:16384
	ds_read_b128 v[190:193], v153 offset:17408
	ds_read_b128 v[194:197], v153 offset:18432
	ds_read_b128 v[198:201], v153 offset:19456
	ds_read_b128 v[202:205], v153 offset:20480
	ds_read_b128 v[206:209], v153 offset:21504
	ds_read_b128 v[210:213], v153 offset:22528
	ds_read_b128 v[214:217], v153 offset:23552
	global_load_lds_dwordx4 v132, s[26:27]
	s_add_i32 m0, s50, 0x2000
	s_add_u32 s50, s26, 0x80000
	s_addc_u32 s51, s27, 0
	s_add_i32 s52, s43, s35
	global_load_lds_dwordx4 v136, s[26:27]
	s_mov_b32 m0, s52
	s_nop 0
	global_load_lds_dwordx4 v132, s[50:51]
	s_add_i32 m0, s52, 0x2000
	s_nop 0
	global_load_lds_dwordx4 v136, s[50:51]
	s_mov_b32 m0, s11
	s_nop 0
	global_load_lds_dwordx4 v130, s[28:29]
	s_mov_b32 m0, s36
	s_nop 0
	global_load_lds_dwordx4 v134, s[28:29]
	s_waitcnt vmcnt(8)
	s_waitcnt lgkmcnt(0)
	s_barrier
	s_waitcnt lgkmcnt(0)
	v_mfma_f32_16x16x32_bf16 v[60:63], v[154:157], v[186:189], v[60:63]
	v_mfma_f32_16x16x32_bf16 v[60:63], v[158:161], v[190:193], v[60:63]
	v_mfma_f32_16x16x32_bf16 v[56:59], v[162:165], v[186:189], v[56:59]
	v_mfma_f32_16x16x32_bf16 v[56:59], v[166:169], v[190:193], v[56:59]
	v_mfma_f32_16x16x32_bf16 v[40:43], v[162:165], v[194:197], v[40:43]
	v_mfma_f32_16x16x32_bf16 v[40:43], v[166:169], v[198:201], v[40:43]
	v_mfma_f32_16x16x32_bf16 v[44:47], v[154:157], v[194:197], v[44:47]
	v_mfma_f32_16x16x32_bf16 v[44:47], v[158:161], v[198:201], v[44:47]
	v_mfma_f32_16x16x32_bf16 v[28:31], v[154:157], v[202:205], v[28:31]
	v_mfma_f32_16x16x32_bf16 v[28:31], v[158:161], v[206:209], v[28:31]
	v_mfma_f32_16x16x32_bf16 v[24:27], v[162:165], v[202:205], v[24:27]
	v_mfma_f32_16x16x32_bf16 v[24:27], v[166:169], v[206:209], v[24:27]
	v_mfma_f32_16x16x32_bf16 v[8:11], v[162:165], v[210:213], v[8:11]
	v_mfma_f32_16x16x32_bf16 v[8:11], v[166:169], v[214:217], v[8:11]
	v_mfma_f32_16x16x32_bf16 v[12:15], v[154:157], v[210:213], v[12:15]
	v_mfma_f32_16x16x32_bf16 v[12:15], v[158:161], v[214:217], v[12:15]
	v_mfma_f32_16x16x32_bf16 v[52:55], v[170:173], v[186:189], v[52:55]
	v_mfma_f32_16x16x32_bf16 v[52:55], v[174:177], v[190:193], v[52:55]
	v_mfma_f32_16x16x32_bf16 v[48:51], v[178:181], v[186:189], v[48:51]
	v_mfma_f32_16x16x32_bf16 v[48:51], v[182:185], v[190:193], v[48:51]
	v_mfma_f32_16x16x32_bf16 v[32:35], v[178:181], v[194:197], v[32:35]
	v_mfma_f32_16x16x32_bf16 v[32:35], v[182:185], v[198:201], v[32:35]
	v_mfma_f32_16x16x32_bf16 v[36:39], v[170:173], v[194:197], v[36:39]
	v_mfma_f32_16x16x32_bf16 v[36:39], v[174:177], v[198:201], v[36:39]
	v_mfma_f32_16x16x32_bf16 v[20:23], v[170:173], v[202:205], v[20:23]
	v_mfma_f32_16x16x32_bf16 v[20:23], v[174:177], v[206:209], v[20:23]
	v_mfma_f32_16x16x32_bf16 v[16:19], v[178:181], v[202:205], v[16:19]
	v_mfma_f32_16x16x32_bf16 v[16:19], v[182:185], v[206:209], v[16:19]
	v_mfma_f32_16x16x32_bf16 v[0:3], v[178:181], v[210:213], v[0:3]
	v_mfma_f32_16x16x32_bf16 v[0:3], v[182:185], v[214:217], v[0:3]
	v_mfma_f32_16x16x32_bf16 v[4:7], v[170:173], v[210:213], v[4:7]
	v_mfma_f32_16x16x32_bf16 v[4:7], v[174:177], v[214:217], v[4:7]
	s_barrier
	s_add_i32 s50, 0, 0x18000
	s_add_i32 s51, 0, 0x1c000
	v_add_u32_e32 v166, s50, v152
	v_add_u32_e32 v182, s51, v152
	ds_read_b128 v[154:157], v166
	ds_read_b128 v[158:161], v166 offset:1024
	ds_read_b128 v[162:165], v166 offset:2048
	ds_read_b128 v[166:169], v166 offset:3072
	ds_read_b128 v[170:173], v182
	ds_read_b128 v[174:177], v182 offset:1024
	ds_read_b128 v[178:181], v182 offset:2048
	ds_read_b128 v[182:185], v182 offset:3072
	s_add_u32 s28, s28, 0x80000
	s_addc_u32 s29, s29, 0
	s_mov_b32 m0, s37
	ds_read_b128 v[186:189], v153 offset:32768
	ds_read_b128 v[190:193], v153 offset:33792
	ds_read_b128 v[194:197], v153 offset:34816
	ds_read_b128 v[198:201], v153 offset:35840
	ds_read_b128 v[202:205], v153 offset:36864
	ds_read_b128 v[206:209], v153 offset:37888
	ds_read_b128 v[210:213], v153 offset:38912
	ds_read_b128 v[214:217], v153 offset:39936
	global_load_lds_dwordx4 v130, s[28:29]
	s_mov_b32 m0, s38
	s_nop 0
	global_load_lds_dwordx4 v134, s[28:29]
	s_waitcnt vmcnt(8)
	s_waitcnt lgkmcnt(0)
	s_barrier
	s_waitcnt lgkmcnt(0)
	v_mfma_f32_16x16x32_bf16 v[124:127], v[154:157], v[186:189], v[124:127]
	v_mfma_f32_16x16x32_bf16 v[124:127], v[158:161], v[190:193], v[124:127]
	v_mfma_f32_16x16x32_bf16 v[120:123], v[162:165], v[186:189], v[120:123]
	v_mfma_f32_16x16x32_bf16 v[120:123], v[166:169], v[190:193], v[120:123]
	v_mfma_f32_16x16x32_bf16 v[104:107], v[162:165], v[194:197], v[104:107]
	v_mfma_f32_16x16x32_bf16 v[104:107], v[166:169], v[198:201], v[104:107]
	v_mfma_f32_16x16x32_bf16 v[108:111], v[154:157], v[194:197], v[108:111]
	v_mfma_f32_16x16x32_bf16 v[108:111], v[158:161], v[198:201], v[108:111]
	v_mfma_f32_16x16x32_bf16 v[92:95], v[154:157], v[202:205], v[92:95]
	v_mfma_f32_16x16x32_bf16 v[92:95], v[158:161], v[206:209], v[92:95]
	v_mfma_f32_16x16x32_bf16 v[88:91], v[162:165], v[202:205], v[88:91]
	v_mfma_f32_16x16x32_bf16 v[88:91], v[166:169], v[206:209], v[88:91]
	v_mfma_f32_16x16x32_bf16 v[72:75], v[162:165], v[210:213], v[72:75]
	v_mfma_f32_16x16x32_bf16 v[72:75], v[166:169], v[214:217], v[72:75]
	v_mfma_f32_16x16x32_bf16 v[76:79], v[154:157], v[210:213], v[76:79]
	v_mfma_f32_16x16x32_bf16 v[76:79], v[158:161], v[214:217], v[76:79]
	v_mfma_f32_16x16x32_bf16 v[116:119], v[170:173], v[186:189], v[116:119]
	v_mfma_f32_16x16x32_bf16 v[116:119], v[174:177], v[190:193], v[116:119]
	v_mfma_f32_16x16x32_bf16 v[112:115], v[178:181], v[186:189], v[112:115]
	v_mfma_f32_16x16x32_bf16 v[112:115], v[182:185], v[190:193], v[112:115]
	v_mfma_f32_16x16x32_bf16 v[96:99], v[178:181], v[194:197], v[96:99]
	v_mfma_f32_16x16x32_bf16 v[96:99], v[182:185], v[198:201], v[96:99]
	v_mfma_f32_16x16x32_bf16 v[100:103], v[170:173], v[194:197], v[100:103]
	v_mfma_f32_16x16x32_bf16 v[100:103], v[174:177], v[198:201], v[100:103]
	v_mfma_f32_16x16x32_bf16 v[84:87], v[170:173], v[202:205], v[84:87]
	v_mfma_f32_16x16x32_bf16 v[84:87], v[174:177], v[206:209], v[84:87]
	v_mfma_f32_16x16x32_bf16 v[80:83], v[178:181], v[202:205], v[80:83]
	v_mfma_f32_16x16x32_bf16 v[80:83], v[182:185], v[206:209], v[80:83]
	v_mfma_f32_16x16x32_bf16 v[64:67], v[178:181], v[210:213], v[64:67]
	v_mfma_f32_16x16x32_bf16 v[64:67], v[182:185], v[214:217], v[64:67]
	v_mfma_f32_16x16x32_bf16 v[68:71], v[170:173], v[210:213], v[68:71]
	v_mfma_f32_16x16x32_bf16 v[68:71], v[174:177], v[214:217], v[68:71]
	s_barrier
	s_add_i32 s28, s50, s35
	s_add_u32 s98, s26, 0x80
	s_addc_u32 s99, s27, 0
	s_mov_b32 m0, s28
	ds_read_b128 v[186:189], v153 offset:49152
	ds_read_b128 v[190:193], v153 offset:50176
	ds_read_b128 v[194:197], v153 offset:51200
	ds_read_b128 v[198:201], v153 offset:52224
	ds_read_b128 v[202:205], v153 offset:53248
	ds_read_b128 v[206:209], v153 offset:54272
	ds_read_b128 v[210:213], v153 offset:55296
	ds_read_b128 v[214:217], v153 offset:56320
	global_load_lds_dwordx4 v132, s[98:99]
	s_add_i32 m0, s28, 0x2000
	s_add_u32 s26, s26, 0x80080
	s_addc_u32 s27, s27, 0
	s_add_i32 s28, s51, s35
	global_load_lds_dwordx4 v136, s[98:99]
	s_mov_b32 m0, s28
	s_nop 0
	global_load_lds_dwordx4 v132, s[26:27]
	s_add_i32 m0, s28, 0x2000
	s_nop 0
	global_load_lds_dwordx4 v136, s[26:27]
	s_mov_b32 m0, s39
	s_nop 0
	global_load_lds_dwordx4 v130, s[100:101]
	s_mov_b32 m0, s40
	s_nop 0
	global_load_lds_dwordx4 v134, s[100:101]
	s_waitcnt vmcnt(8)
	s_waitcnt lgkmcnt(0)
	s_barrier
	s_waitcnt lgkmcnt(0)
	v_mfma_f32_16x16x32_bf16 v[60:63], v[154:157], v[186:189], v[60:63]
	v_mfma_f32_16x16x32_bf16 v[60:63], v[158:161], v[190:193], v[60:63]
	v_mfma_f32_16x16x32_bf16 v[56:59], v[162:165], v[186:189], v[56:59]
	v_mfma_f32_16x16x32_bf16 v[56:59], v[166:169], v[190:193], v[56:59]
	v_mfma_f32_16x16x32_bf16 v[40:43], v[162:165], v[194:197], v[40:43]
	v_mfma_f32_16x16x32_bf16 v[40:43], v[166:169], v[198:201], v[40:43]
	v_mfma_f32_16x16x32_bf16 v[44:47], v[154:157], v[194:197], v[44:47]
	v_mfma_f32_16x16x32_bf16 v[44:47], v[158:161], v[198:201], v[44:47]
	v_mfma_f32_16x16x32_bf16 v[28:31], v[154:157], v[202:205], v[28:31]
	v_mfma_f32_16x16x32_bf16 v[28:31], v[158:161], v[206:209], v[28:31]
	v_mfma_f32_16x16x32_bf16 v[24:27], v[162:165], v[202:205], v[24:27]
	v_mfma_f32_16x16x32_bf16 v[24:27], v[166:169], v[206:209], v[24:27]
	v_mfma_f32_16x16x32_bf16 v[8:11], v[162:165], v[210:213], v[8:11]
	v_mfma_f32_16x16x32_bf16 v[8:11], v[166:169], v[214:217], v[8:11]
	v_mfma_f32_16x16x32_bf16 v[12:15], v[154:157], v[210:213], v[12:15]
	v_mfma_f32_16x16x32_bf16 v[12:15], v[158:161], v[214:217], v[12:15]
	v_mfma_f32_16x16x32_bf16 v[52:55], v[170:173], v[186:189], v[52:55]
	v_mfma_f32_16x16x32_bf16 v[52:55], v[174:177], v[190:193], v[52:55]
	v_mfma_f32_16x16x32_bf16 v[48:51], v[178:181], v[186:189], v[48:51]
	v_mfma_f32_16x16x32_bf16 v[48:51], v[182:185], v[190:193], v[48:51]
	v_mfma_f32_16x16x32_bf16 v[32:35], v[178:181], v[194:197], v[32:35]
	v_mfma_f32_16x16x32_bf16 v[32:35], v[182:185], v[198:201], v[32:35]
	v_mfma_f32_16x16x32_bf16 v[36:39], v[170:173], v[194:197], v[36:39]
	v_mfma_f32_16x16x32_bf16 v[36:39], v[174:177], v[198:201], v[36:39]
	v_mfma_f32_16x16x32_bf16 v[20:23], v[170:173], v[202:205], v[20:23]
	v_mfma_f32_16x16x32_bf16 v[20:23], v[174:177], v[206:209], v[20:23]
	v_mfma_f32_16x16x32_bf16 v[16:19], v[178:181], v[202:205], v[16:19]
	v_mfma_f32_16x16x32_bf16 v[16:19], v[182:185], v[206:209], v[16:19]
	v_mfma_f32_16x16x32_bf16 v[0:3], v[178:181], v[210:213], v[0:3]
	v_mfma_f32_16x16x32_bf16 v[0:3], v[182:185], v[214:217], v[0:3]
	v_mfma_f32_16x16x32_bf16 v[4:7], v[170:173], v[210:213], v[4:7]
	v_mfma_f32_16x16x32_bf16 v[4:7], v[174:177], v[214:217], v[4:7]
	s_barrier
	s_add_i32 s49, s49, 2
	s_add_u32 s24, s24, 0x100
	s_addc_u32 s25, s25, 0
	s_cmp_gt_u32 s49, 29
	s_cbranch_scc0 .LBB0_585
	s_add_u32 s24, s45, 0xffffff00
	s_addc_u32 s25, s46, -1
	s_andn2_b64 vcc, exec, s[4:5]
	s_cbranch_vccnz .LBB0_588
	v_mov_b32_e32 v0, 0
	s_mov_b32 s8, s16
	s_mov_b32 s10, s18
	s_mov_b64 s[12:13], s[22:23]
	s_mov_b32 s41, s44
	v_mov_b32_e32 v1, v0
	v_mov_b32_e32 v2, v0
	v_mov_b32_e32 v3, v0
	v_mov_b32_e32 v4, v0
	v_mov_b32_e32 v5, v0
	v_mov_b32_e32 v6, v0
	v_mov_b32_e32 v7, v0
	v_mov_b32_e32 v16, v0
	v_mov_b32_e32 v17, v0
	v_mov_b32_e32 v18, v0
	v_mov_b32_e32 v19, v0
	v_mov_b32_e32 v20, v0
	v_mov_b32_e32 v21, v0
	v_mov_b32_e32 v22, v0
	v_mov_b32_e32 v23, v0
	v_mov_b32_e32 v32, v0
	v_mov_b32_e32 v33, v0
	v_mov_b32_e32 v34, v0
	v_mov_b32_e32 v35, v0
	v_mov_b32_e32 v36, v0
	v_mov_b32_e32 v37, v0
	v_mov_b32_e32 v38, v0
	v_mov_b32_e32 v39, v0
	v_mov_b32_e32 v48, v0
	v_mov_b32_e32 v49, v0
	v_mov_b32_e32 v50, v0
	v_mov_b32_e32 v51, v0
	v_mov_b32_e32 v52, v0
	v_mov_b32_e32 v53, v0
	v_mov_b32_e32 v54, v0
	v_mov_b32_e32 v55, v0
	v_mov_b32_e32 v8, v0
	v_mov_b32_e32 v9, v0
	v_mov_b32_e32 v10, v0
	v_mov_b32_e32 v11, v0
	v_mov_b32_e32 v12, v0
	v_mov_b32_e32 v13, v0
	v_mov_b32_e32 v14, v0
	v_mov_b32_e32 v15, v0
	v_mov_b32_e32 v24, v0
	v_mov_b32_e32 v25, v0
	v_mov_b32_e32 v26, v0
	v_mov_b32_e32 v27, v0
	v_mov_b32_e32 v28, v0
	v_mov_b32_e32 v29, v0
	v_mov_b32_e32 v30, v0
	v_mov_b32_e32 v31, v0
	v_mov_b32_e32 v40, v0
	v_mov_b32_e32 v41, v0
	v_mov_b32_e32 v42, v0
	v_mov_b32_e32 v43, v0
	v_mov_b32_e32 v44, v0
	v_mov_b32_e32 v45, v0
	v_mov_b32_e32 v46, v0
	v_mov_b32_e32 v47, v0
	v_mov_b32_e32 v56, v0
	v_mov_b32_e32 v57, v0
	v_mov_b32_e32 v58, v0
	v_mov_b32_e32 v59, v0
	v_mov_b32_e32 v60, v0
	v_mov_b32_e32 v61, v0
	v_mov_b32_e32 v62, v0
	v_mov_b32_e32 v63, v0
	v_mov_b32_e32 v64, v0
	v_mov_b32_e32 v65, v0
	v_mov_b32_e32 v66, v0
	v_mov_b32_e32 v67, v0
	v_mov_b32_e32 v68, v0
	v_mov_b32_e32 v69, v0
	v_mov_b32_e32 v70, v0
	v_mov_b32_e32 v71, v0
	v_mov_b32_e32 v80, v0
	v_mov_b32_e32 v81, v0
	v_mov_b32_e32 v82, v0
	v_mov_b32_e32 v83, v0
	v_mov_b32_e32 v84, v0
	v_mov_b32_e32 v85, v0
	v_mov_b32_e32 v86, v0
	v_mov_b32_e32 v87, v0
	v_mov_b32_e32 v96, v0
	v_mov_b32_e32 v97, v0
	v_mov_b32_e32 v98, v0
	v_mov_b32_e32 v99, v0
	v_mov_b32_e32 v100, v0
	v_mov_b32_e32 v101, v0
	v_mov_b32_e32 v102, v0
	v_mov_b32_e32 v103, v0
	v_mov_b32_e32 v112, v0
	v_mov_b32_e32 v113, v0
	v_mov_b32_e32 v114, v0
	v_mov_b32_e32 v115, v0
	v_mov_b32_e32 v116, v0
	v_mov_b32_e32 v117, v0
	v_mov_b32_e32 v118, v0
	v_mov_b32_e32 v119, v0
	v_mov_b32_e32 v72, v0
	v_mov_b32_e32 v73, v0
	v_mov_b32_e32 v74, v0
	v_mov_b32_e32 v75, v0
	v_mov_b32_e32 v76, v0
	v_mov_b32_e32 v77, v0
	v_mov_b32_e32 v78, v0
	v_mov_b32_e32 v79, v0
	v_mov_b32_e32 v88, v0
	v_mov_b32_e32 v89, v0
	v_mov_b32_e32 v90, v0
	v_mov_b32_e32 v91, v0
	v_mov_b32_e32 v92, v0
	v_mov_b32_e32 v93, v0
	v_mov_b32_e32 v94, v0
	v_mov_b32_e32 v95, v0
	v_mov_b32_e32 v104, v0
	v_mov_b32_e32 v105, v0
	v_mov_b32_e32 v106, v0
	v_mov_b32_e32 v107, v0
	v_mov_b32_e32 v108, v0
	v_mov_b32_e32 v109, v0
	v_mov_b32_e32 v110, v0
	v_mov_b32_e32 v111, v0
	v_mov_b32_e32 v120, v0
	v_mov_b32_e32 v121, v0
	v_mov_b32_e32 v122, v0
	v_mov_b32_e32 v123, v0
	v_mov_b32_e32 v124, v0
	v_mov_b32_e32 v125, v0
	v_mov_b32_e32 v126, v0
	v_mov_b32_e32 v127, v0
	s_andn2_b64 vcc, exec, s[0:1]
	s_cbranch_vccnz .LBB0_589
	s_branch .LBB0_590

.LBB0_671:
	ds_read_b128 v[156:159], v151
	ds_read_b128 v[160:163], v151 offset:1024
	ds_read_b128 v[164:167], v151 offset:2048
	ds_read_b128 v[168:171], v151 offset:3072
	ds_read_b128 v[172:175], v152
	ds_read_b128 v[176:179], v152 offset:1024
	ds_read_b128 v[180:183], v152 offset:2048
	ds_read_b128 v[184:187], v152 offset:3072
	s_add_u32 s28, s26, 0xfff80080
	s_addc_u32 s29, s27, -1
	s_cmp_eq_u32 s53, 28
	s_cselect_b32 s31, s19, s29
	s_cselect_b32 s30, s49, s28
	s_cselect_b32 s29, s17, s52
	s_cselect_b32 s28, s50, s51
	s_add_u32 s100, s30, 0x80
	s_addc_u32 s101, s31, 0
	s_add_i32 m0, s25, 0xc000
	ds_read_b128 v[188:191], v153
	ds_read_b128 v[192:195], v153 offset:1024
	ds_read_b128 v[196:199], v153 offset:2048
	ds_read_b128 v[200:203], v153 offset:3072
	ds_read_b128 v[204:207], v153 offset:4096
	ds_read_b128 v[208:211], v153 offset:5120
	ds_read_b128 v[212:215], v153 offset:6144
	ds_read_b128 v[216:219], v153 offset:7168
	global_load_lds_dwordx4 v138, s[26:27]
	s_add_i32 m0, s25, 0xe000
	s_nop 0
	global_load_lds_dwordx4 v140, s[26:27]
	s_waitcnt vmcnt(8)
	s_waitcnt lgkmcnt(0)
	s_barrier
	s_waitcnt lgkmcnt(0)
	v_mfma_f32_16x16x32_bf16 v[116:119], v[156:159], v[188:191], v[116:119]
	v_mfma_f32_16x16x32_bf16 v[116:119], v[160:163], v[192:195], v[116:119]
	v_mfma_f32_16x16x32_bf16 v[112:115], v[164:167], v[188:191], v[112:115]
	v_mfma_f32_16x16x32_bf16 v[112:115], v[168:171], v[192:195], v[112:115]
	v_mfma_f32_16x16x32_bf16 v[96:99], v[164:167], v[196:199], v[96:99]
	v_mfma_f32_16x16x32_bf16 v[96:99], v[168:171], v[200:203], v[96:99]
	v_mfma_f32_16x16x32_bf16 v[100:103], v[156:159], v[196:199], v[100:103]
	v_mfma_f32_16x16x32_bf16 v[100:103], v[160:163], v[200:203], v[100:103]
	v_mfma_f32_16x16x32_bf16 v[84:87], v[156:159], v[204:207], v[84:87]
	v_mfma_f32_16x16x32_bf16 v[84:87], v[160:163], v[208:211], v[84:87]
	v_mfma_f32_16x16x32_bf16 v[80:83], v[164:167], v[204:207], v[80:83]
	v_mfma_f32_16x16x32_bf16 v[80:83], v[168:171], v[208:211], v[80:83]
	v_mfma_f32_16x16x32_bf16 v[64:67], v[164:167], v[212:215], v[64:67]
	v_mfma_f32_16x16x32_bf16 v[64:67], v[168:171], v[216:219], v[64:67]
	v_mfma_f32_16x16x32_bf16 v[68:71], v[156:159], v[212:215], v[68:71]
	v_mfma_f32_16x16x32_bf16 v[68:71], v[160:163], v[216:219], v[68:71]
	v_mfma_f32_16x16x32_bf16 v[124:127], v[172:175], v[188:191], v[124:127]
	v_mfma_f32_16x16x32_bf16 v[124:127], v[176:179], v[192:195], v[124:127]
	v_mfma_f32_16x16x32_bf16 v[120:123], v[180:183], v[188:191], v[120:123]
	v_mfma_f32_16x16x32_bf16 v[120:123], v[184:187], v[192:195], v[120:123]
	v_mfma_f32_16x16x32_bf16 v[104:107], v[180:183], v[196:199], v[104:107]
	v_mfma_f32_16x16x32_bf16 v[104:107], v[184:187], v[200:203], v[104:107]
	v_mfma_f32_16x16x32_bf16 v[108:111], v[172:175], v[196:199], v[108:111]
	v_mfma_f32_16x16x32_bf16 v[108:111], v[176:179], v[200:203], v[108:111]
	v_mfma_f32_16x16x32_bf16 v[92:95], v[172:175], v[204:207], v[92:95]
	v_mfma_f32_16x16x32_bf16 v[92:95], v[176:179], v[208:211], v[92:95]
	v_mfma_f32_16x16x32_bf16 v[88:91], v[180:183], v[204:207], v[88:91]
	v_mfma_f32_16x16x32_bf16 v[88:91], v[184:187], v[208:211], v[88:91]
	v_mfma_f32_16x16x32_bf16 v[72:75], v[180:183], v[212:215], v[72:75]
	v_mfma_f32_16x16x32_bf16 v[72:75], v[184:187], v[216:219], v[72:75]
	v_mfma_f32_16x16x32_bf16 v[76:79], v[172:175], v[212:215], v[76:79]
	v_mfma_f32_16x16x32_bf16 v[76:79], v[176:179], v[216:219], v[76:79]
	s_barrier
	s_add_i32 s54, s46, s36
	s_mov_b32 m0, s54
	ds_read_b128 v[188:191], v153 offset:16384
	ds_read_b128 v[192:195], v153 offset:17408
	ds_read_b128 v[196:199], v153 offset:18432
	ds_read_b128 v[200:203], v153 offset:19456
	ds_read_b128 v[204:207], v153 offset:20480
	ds_read_b128 v[208:211], v153 offset:21504
	ds_read_b128 v[212:215], v153 offset:22528
	ds_read_b128 v[216:219], v153 offset:23552
	global_load_lds_dwordx4 v134, s[28:29]
	s_add_i32 m0, s54, 0x2000
	s_add_u32 s54, s28, 0x80000
	s_addc_u32 s55, s29, 0
	s_add_i32 s56, s47, s36
	global_load_lds_dwordx4 v130, s[28:29]
	s_mov_b32 m0, s56
	s_nop 0
	global_load_lds_dwordx4 v134, s[54:55]
	s_add_i32 m0, s56, 0x2000
	s_nop 0
	global_load_lds_dwordx4 v130, s[54:55]
	s_mov_b32 m0, s25
	s_nop 0
	global_load_lds_dwordx4 v136, s[30:31]
	s_mov_b32 m0, s39
	s_nop 0
	global_load_lds_dwordx4 v132, s[30:31]
	s_waitcnt vmcnt(8)
	s_waitcnt lgkmcnt(0)
	s_barrier
	s_waitcnt lgkmcnt(0)
	v_mfma_f32_16x16x32_bf16 v[52:55], v[156:159], v[188:191], v[52:55]
	v_mfma_f32_16x16x32_bf16 v[52:55], v[160:163], v[192:195], v[52:55]
	v_mfma_f32_16x16x32_bf16 v[48:51], v[164:167], v[188:191], v[48:51]
	v_mfma_f32_16x16x32_bf16 v[48:51], v[168:171], v[192:195], v[48:51]
	v_mfma_f32_16x16x32_bf16 v[32:35], v[164:167], v[196:199], v[32:35]
	v_mfma_f32_16x16x32_bf16 v[32:35], v[168:171], v[200:203], v[32:35]
	v_mfma_f32_16x16x32_bf16 v[36:39], v[156:159], v[196:199], v[36:39]
	v_mfma_f32_16x16x32_bf16 v[36:39], v[160:163], v[200:203], v[36:39]
	v_mfma_f32_16x16x32_bf16 v[20:23], v[156:159], v[204:207], v[20:23]
	v_mfma_f32_16x16x32_bf16 v[20:23], v[160:163], v[208:211], v[20:23]
	v_mfma_f32_16x16x32_bf16 v[16:19], v[164:167], v[204:207], v[16:19]
	v_mfma_f32_16x16x32_bf16 v[16:19], v[168:171], v[208:211], v[16:19]
	v_mfma_f32_16x16x32_bf16 v[0:3], v[164:167], v[212:215], v[0:3]
	v_mfma_f32_16x16x32_bf16 v[0:3], v[168:171], v[216:219], v[0:3]
	v_mfma_f32_16x16x32_bf16 v[8:11], v[156:159], v[212:215], v[8:11]
	v_mfma_f32_16x16x32_bf16 v[8:11], v[160:163], v[216:219], v[8:11]
	v_mfma_f32_16x16x32_bf16 v[60:63], v[172:175], v[188:191], v[60:63]
	v_mfma_f32_16x16x32_bf16 v[60:63], v[176:179], v[192:195], v[60:63]
	v_mfma_f32_16x16x32_bf16 v[56:59], v[180:183], v[188:191], v[56:59]
	v_mfma_f32_16x16x32_bf16 v[56:59], v[184:187], v[192:195], v[56:59]
	v_mfma_f32_16x16x32_bf16 v[40:43], v[180:183], v[196:199], v[40:43]
	v_mfma_f32_16x16x32_bf16 v[40:43], v[184:187], v[200:203], v[40:43]
	v_mfma_f32_16x16x32_bf16 v[44:47], v[172:175], v[196:199], v[44:47]
	v_mfma_f32_16x16x32_bf16 v[44:47], v[176:179], v[200:203], v[44:47]
	v_mfma_f32_16x16x32_bf16 v[28:31], v[172:175], v[204:207], v[28:31]
	v_mfma_f32_16x16x32_bf16 v[28:31], v[176:179], v[208:211], v[28:31]
	v_mfma_f32_16x16x32_bf16 v[24:27], v[180:183], v[204:207], v[24:27]
	v_mfma_f32_16x16x32_bf16 v[24:27], v[184:187], v[208:211], v[24:27]
	v_mfma_f32_16x16x32_bf16 v[4:7], v[180:183], v[212:215], v[4:7]
	v_mfma_f32_16x16x32_bf16 v[4:7], v[184:187], v[216:219], v[4:7]
	v_mfma_f32_16x16x32_bf16 v[12:15], v[172:175], v[212:215], v[12:15]
	v_mfma_f32_16x16x32_bf16 v[12:15], v[176:179], v[216:219], v[12:15]
	s_barrier
	s_add_i32 s54, 0, 0x18000
	v_add_u32_e32 v155, s54, v149
	s_add_i32 s55, 0, 0x1c000
	ds_read_b128 v[156:159], v155
	ds_read_b128 v[160:163], v155 offset:1024
	ds_read_b128 v[164:167], v155 offset:2048
	ds_read_b128 v[168:171], v155 offset:3072
	v_add_u32_e32 v155, s55, v149
	ds_read_b128 v[172:175], v155
	ds_read_b128 v[176:179], v155 offset:1024
	ds_read_b128 v[180:183], v155 offset:2048
	ds_read_b128 v[184:187], v155 offset:3072
	s_add_u32 s30, s30, 0x80000
	s_addc_u32 s31, s31, 0
	s_mov_b32 m0, s40
	ds_read_b128 v[188:191], v153 offset:32768
	ds_read_b128 v[192:195], v153 offset:33792
	ds_read_b128 v[196:199], v153 offset:34816
	ds_read_b128 v[200:203], v153 offset:35840
	ds_read_b128 v[204:207], v153 offset:36864
	ds_read_b128 v[208:211], v153 offset:37888
	ds_read_b128 v[212:215], v153 offset:38912
	ds_read_b128 v[216:219], v153 offset:39936
	global_load_lds_dwordx4 v136, s[30:31]
	s_mov_b32 m0, s41
	s_nop 0
	global_load_lds_dwordx4 v132, s[30:31]
	s_waitcnt vmcnt(8)
	s_waitcnt lgkmcnt(0)
	s_barrier
	s_waitcnt lgkmcnt(0)
	v_mfma_f32_16x16x32_bf16 v[116:119], v[156:159], v[188:191], v[116:119]
	v_mfma_f32_16x16x32_bf16 v[116:119], v[160:163], v[192:195], v[116:119]
	v_mfma_f32_16x16x32_bf16 v[112:115], v[164:167], v[188:191], v[112:115]
	v_mfma_f32_16x16x32_bf16 v[112:115], v[168:171], v[192:195], v[112:115]
	v_mfma_f32_16x16x32_bf16 v[96:99], v[164:167], v[196:199], v[96:99]
	v_mfma_f32_16x16x32_bf16 v[96:99], v[168:171], v[200:203], v[96:99]
	v_mfma_f32_16x16x32_bf16 v[100:103], v[156:159], v[196:199], v[100:103]
	v_mfma_f32_16x16x32_bf16 v[100:103], v[160:163], v[200:203], v[100:103]
	v_mfma_f32_16x16x32_bf16 v[84:87], v[156:159], v[204:207], v[84:87]
	v_mfma_f32_16x16x32_bf16 v[84:87], v[160:163], v[208:211], v[84:87]
	v_mfma_f32_16x16x32_bf16 v[80:83], v[164:167], v[204:207], v[80:83]
	v_mfma_f32_16x16x32_bf16 v[80:83], v[168:171], v[208:211], v[80:83]
	v_mfma_f32_16x16x32_bf16 v[64:67], v[164:167], v[212:215], v[64:67]
	v_mfma_f32_16x16x32_bf16 v[64:67], v[168:171], v[216:219], v[64:67]
	v_mfma_f32_16x16x32_bf16 v[68:71], v[156:159], v[212:215], v[68:71]
	v_mfma_f32_16x16x32_bf16 v[68:71], v[160:163], v[216:219], v[68:71]
	v_mfma_f32_16x16x32_bf16 v[124:127], v[172:175], v[188:191], v[124:127]
	v_mfma_f32_16x16x32_bf16 v[124:127], v[176:179], v[192:195], v[124:127]
	v_mfma_f32_16x16x32_bf16 v[120:123], v[180:183], v[188:191], v[120:123]
	v_mfma_f32_16x16x32_bf16 v[120:123], v[184:187], v[192:195], v[120:123]
	v_mfma_f32_16x16x32_bf16 v[104:107], v[180:183], v[196:199], v[104:107]
	v_mfma_f32_16x16x32_bf16 v[104:107], v[184:187], v[200:203], v[104:107]
	v_mfma_f32_16x16x32_bf16 v[108:111], v[172:175], v[196:199], v[108:111]
	v_mfma_f32_16x16x32_bf16 v[108:111], v[176:179], v[200:203], v[108:111]
	v_mfma_f32_16x16x32_bf16 v[92:95], v[172:175], v[204:207], v[92:95]
	v_mfma_f32_16x16x32_bf16 v[92:95], v[176:179], v[208:211], v[92:95]
	v_mfma_f32_16x16x32_bf16 v[88:91], v[180:183], v[204:207], v[88:91]
	v_mfma_f32_16x16x32_bf16 v[88:91], v[184:187], v[208:211], v[88:91]
	v_mfma_f32_16x16x32_bf16 v[72:75], v[180:183], v[212:215], v[72:75]
	v_mfma_f32_16x16x32_bf16 v[72:75], v[184:187], v[216:219], v[72:75]
	v_mfma_f32_16x16x32_bf16 v[76:79], v[172:175], v[212:215], v[76:79]
	v_mfma_f32_16x16x32_bf16 v[76:79], v[176:179], v[216:219], v[76:79]
	s_barrier
	s_add_i32 s30, s54, s36
	s_add_u32 s98, s28, 0x80
	s_addc_u32 s99, s29, 0
	s_mov_b32 m0, s30
	ds_read_b128 v[188:191], v153 offset:49152
	ds_read_b128 v[192:195], v153 offset:50176
	ds_read_b128 v[196:199], v153 offset:51200
	ds_read_b128 v[200:203], v153 offset:52224
	ds_read_b128 v[204:207], v153 offset:53248
	ds_read_b128 v[208:211], v153 offset:54272
	ds_read_b128 v[212:215], v153 offset:55296
	ds_read_b128 v[216:219], v153 offset:56320
	global_load_lds_dwordx4 v134, s[98:99]
	s_add_i32 m0, s30, 0x2000
	s_add_u32 s28, s28, 0x80080
	s_addc_u32 s29, s29, 0
	s_add_i32 s30, s55, s36
	global_load_lds_dwordx4 v130, s[98:99]
	s_mov_b32 m0, s30
	s_nop 0
	global_load_lds_dwordx4 v134, s[28:29]
	s_add_i32 m0, s30, 0x2000
	s_nop 0
	global_load_lds_dwordx4 v130, s[28:29]
	s_mov_b32 m0, s43
	s_nop 0
	global_load_lds_dwordx4 v136, s[100:101]
	s_mov_b32 m0, s44
	s_nop 0
	global_load_lds_dwordx4 v132, s[100:101]
	s_waitcnt vmcnt(8)
	s_waitcnt lgkmcnt(0)
	s_barrier
	s_waitcnt lgkmcnt(0)
	v_mfma_f32_16x16x32_bf16 v[52:55], v[156:159], v[188:191], v[52:55]
	v_mfma_f32_16x16x32_bf16 v[52:55], v[160:163], v[192:195], v[52:55]
	v_mfma_f32_16x16x32_bf16 v[48:51], v[164:167], v[188:191], v[48:51]
	v_mfma_f32_16x16x32_bf16 v[48:51], v[168:171], v[192:195], v[48:51]
	v_mfma_f32_16x16x32_bf16 v[32:35], v[164:167], v[196:199], v[32:35]
	v_mfma_f32_16x16x32_bf16 v[32:35], v[168:171], v[200:203], v[32:35]
	v_mfma_f32_16x16x32_bf16 v[36:39], v[156:159], v[196:199], v[36:39]
	v_mfma_f32_16x16x32_bf16 v[36:39], v[160:163], v[200:203], v[36:39]
	v_mfma_f32_16x16x32_bf16 v[20:23], v[156:159], v[204:207], v[20:23]
	v_mfma_f32_16x16x32_bf16 v[20:23], v[160:163], v[208:211], v[20:23]
	v_mfma_f32_16x16x32_bf16 v[16:19], v[164:167], v[204:207], v[16:19]
	v_mfma_f32_16x16x32_bf16 v[16:19], v[168:171], v[208:211], v[16:19]
	v_mfma_f32_16x16x32_bf16 v[0:3], v[164:167], v[212:215], v[0:3]
	v_mfma_f32_16x16x32_bf16 v[0:3], v[168:171], v[216:219], v[0:3]
	v_mfma_f32_16x16x32_bf16 v[8:11], v[156:159], v[212:215], v[8:11]
	v_mfma_f32_16x16x32_bf16 v[8:11], v[160:163], v[216:219], v[8:11]
	v_mfma_f32_16x16x32_bf16 v[60:63], v[172:175], v[188:191], v[60:63]
	v_mfma_f32_16x16x32_bf16 v[60:63], v[176:179], v[192:195], v[60:63]
	v_mfma_f32_16x16x32_bf16 v[56:59], v[180:183], v[188:191], v[56:59]
	v_mfma_f32_16x16x32_bf16 v[56:59], v[184:187], v[192:195], v[56:59]
	v_mfma_f32_16x16x32_bf16 v[40:43], v[180:183], v[196:199], v[40:43]
	v_mfma_f32_16x16x32_bf16 v[40:43], v[184:187], v[200:203], v[40:43]
	v_mfma_f32_16x16x32_bf16 v[44:47], v[172:175], v[196:199], v[44:47]
	v_mfma_f32_16x16x32_bf16 v[44:47], v[176:179], v[200:203], v[44:47]
	v_mfma_f32_16x16x32_bf16 v[28:31], v[172:175], v[204:207], v[28:31]
	v_mfma_f32_16x16x32_bf16 v[28:31], v[176:179], v[208:211], v[28:31]
	v_mfma_f32_16x16x32_bf16 v[24:27], v[180:183], v[204:207], v[24:27]
	v_mfma_f32_16x16x32_bf16 v[24:27], v[184:187], v[208:211], v[24:27]
	v_mfma_f32_16x16x32_bf16 v[4:7], v[180:183], v[212:215], v[4:7]
	v_mfma_f32_16x16x32_bf16 v[4:7], v[184:187], v[216:219], v[4:7]
	v_mfma_f32_16x16x32_bf16 v[12:15], v[172:175], v[212:215], v[12:15]
	v_mfma_f32_16x16x32_bf16 v[12:15], v[176:179], v[216:219], v[12:15]
	s_barrier
	s_add_i32 s53, s53, 2
	s_add_u32 s26, s26, 0x100
	s_addc_u32 s27, s27, 0
	s_add_u32 s51, s51, 0x100
	s_addc_u32 s52, s52, 0
	s_cmp_gt_u32 s53, 29
	s_cbranch_scc0 .LBB0_671
	s_and_b64 vcc, exec, s[14:15]
	s_cbranch_vccz .LBB0_674
	s_barrier

.LBB0_849:
	v_add_u32_e32 v164, s40, v129
	v_add_u32_e32 v173, s41, v129
	s_add_u32 s22, s14, s20
	ds_read_b128 v[152:155], v164
	ds_read_b128 v[156:159], v164 offset:1024
	ds_read_b128 v[160:163], v164 offset:2048
	ds_read_b128 v[164:167], v164 offset:3072
	ds_read_b128 v[168:171], v173
	ds_read_b128 v[174:177], v173 offset:1024
	ds_read_b128 v[178:181], v173 offset:2048
	ds_read_b128 v[182:185], v173 offset:3072
	s_addc_u32 s23, s15, s21
	s_add_u32 s22, s22, 0x100
	s_addc_u32 s23, s23, 0
	s_add_u32 s48, s45, s20
	s_addc_u32 s49, s46, s21
	s_cmpk_eq_i32 s20, 0x2b00
	s_cselect_b32 s25, s19, s23
	s_cselect_b32 s24, s18, s22
	s_cselect_b32 s23, s7, s49
	s_cselect_b32 s22, s6, s48
	s_add_u32 s100, s24, 0x80
	s_addc_u32 s101, s25, 0
	v_lshl_add_u64 v[218:219], v[146:147], 0, s[20:21]
	s_add_i32 m0, s33, 0xc000
	ds_read_b128 v[186:189], v151
	ds_read_b128 v[190:193], v151 offset:1024
	ds_read_b128 v[194:197], v151 offset:2048
	ds_read_b128 v[198:201], v151 offset:3072
	ds_read_b128 v[202:205], v151 offset:4096
	ds_read_b128 v[206:209], v151 offset:5120
	ds_read_b128 v[210:213], v151 offset:6144
	ds_read_b128 v[214:217], v151 offset:7168
	global_load_lds_dwordx4 v[218:219], off
	v_lshl_add_u64 v[218:219], v[148:149], 0, s[20:21]
	s_add_i32 m0, s33, 0xe000
	s_nop 0
	global_load_lds_dwordx4 v[218:219], off
	s_waitcnt vmcnt(8)
	s_waitcnt lgkmcnt(0)
	s_barrier
	s_waitcnt lgkmcnt(0)
	v_mfma_f32_16x16x32_bf16 v[124:127], v[152:155], v[186:189], v[124:127]
	v_mfma_f32_16x16x32_bf16 v[124:127], v[156:159], v[190:193], v[124:127]
	v_mfma_f32_16x16x32_bf16 v[120:123], v[160:163], v[186:189], v[120:123]
	v_mfma_f32_16x16x32_bf16 v[120:123], v[164:167], v[190:193], v[120:123]
	v_mfma_f32_16x16x32_bf16 v[104:107], v[160:163], v[194:197], v[104:107]
	v_mfma_f32_16x16x32_bf16 v[104:107], v[164:167], v[198:201], v[104:107]
	v_mfma_f32_16x16x32_bf16 v[108:111], v[152:155], v[194:197], v[108:111]
	v_mfma_f32_16x16x32_bf16 v[108:111], v[156:159], v[198:201], v[108:111]
	v_mfma_f32_16x16x32_bf16 v[92:95], v[152:155], v[202:205], v[92:95]
	v_mfma_f32_16x16x32_bf16 v[92:95], v[156:159], v[206:209], v[92:95]
	v_mfma_f32_16x16x32_bf16 v[88:91], v[160:163], v[202:205], v[88:91]
	v_mfma_f32_16x16x32_bf16 v[88:91], v[164:167], v[206:209], v[88:91]
	v_mfma_f32_16x16x32_bf16 v[72:75], v[160:163], v[210:213], v[72:75]
	v_mfma_f32_16x16x32_bf16 v[72:75], v[164:167], v[214:217], v[72:75]
	v_mfma_f32_16x16x32_bf16 v[76:79], v[152:155], v[210:213], v[76:79]
	v_mfma_f32_16x16x32_bf16 v[76:79], v[156:159], v[214:217], v[76:79]
	v_mfma_f32_16x16x32_bf16 v[116:119], v[168:171], v[186:189], v[116:119]
	v_mfma_f32_16x16x32_bf16 v[116:119], v[174:177], v[190:193], v[116:119]
	v_mfma_f32_16x16x32_bf16 v[112:115], v[178:181], v[186:189], v[112:115]
	v_mfma_f32_16x16x32_bf16 v[112:115], v[182:185], v[190:193], v[112:115]
	v_mfma_f32_16x16x32_bf16 v[96:99], v[178:181], v[194:197], v[96:99]
	v_mfma_f32_16x16x32_bf16 v[96:99], v[182:185], v[198:201], v[96:99]
	v_mfma_f32_16x16x32_bf16 v[100:103], v[168:171], v[194:197], v[100:103]
	v_mfma_f32_16x16x32_bf16 v[100:103], v[174:177], v[198:201], v[100:103]
	v_mfma_f32_16x16x32_bf16 v[84:87], v[168:171], v[202:205], v[84:87]
	v_mfma_f32_16x16x32_bf16 v[84:87], v[174:177], v[206:209], v[84:87]
	v_mfma_f32_16x16x32_bf16 v[80:83], v[178:181], v[202:205], v[80:83]
	v_mfma_f32_16x16x32_bf16 v[80:83], v[182:185], v[206:209], v[80:83]
	v_mfma_f32_16x16x32_bf16 v[64:67], v[178:181], v[210:213], v[64:67]
	v_mfma_f32_16x16x32_bf16 v[64:67], v[182:185], v[214:217], v[64:67]
	v_mfma_f32_16x16x32_bf16 v[68:71], v[168:171], v[210:213], v[68:71]
	v_mfma_f32_16x16x32_bf16 v[68:71], v[174:177], v[214:217], v[68:71]
	s_barrier
	s_add_i32 s48, s40, s31
	s_mov_b32 m0, s48
	ds_read_b128 v[186:189], v151 offset:16384
	ds_read_b128 v[190:193], v151 offset:17408
	ds_read_b128 v[194:197], v151 offset:18432
	ds_read_b128 v[198:201], v151 offset:19456
	ds_read_b128 v[202:205], v151 offset:20480
	ds_read_b128 v[206:209], v151 offset:21504
	ds_read_b128 v[210:213], v151 offset:22528
	ds_read_b128 v[214:217], v151 offset:23552
	global_load_lds_dwordx4 v132, s[22:23]
	s_add_i32 m0, s48, 0x2000
	s_add_u32 s48, s22, 0x160000
	s_addc_u32 s49, s23, 0
	s_add_i32 s50, s41, s31
	global_load_lds_dwordx4 v136, s[22:23]
	s_mov_b32 m0, s50
	s_nop 0
	global_load_lds_dwordx4 v132, s[48:49]
	s_add_i32 m0, s50, 0x2000
	s_nop 0
	global_load_lds_dwordx4 v136, s[48:49]
	s_mov_b32 m0, s33
	s_nop 0
	global_load_lds_dwordx4 v130, s[24:25]
	s_mov_b32 m0, s34
	s_nop 0
	global_load_lds_dwordx4 v134, s[24:25]
	s_waitcnt vmcnt(8)
	s_waitcnt lgkmcnt(0)
	s_barrier
	s_waitcnt lgkmcnt(0)
	v_mfma_f32_16x16x32_bf16 v[60:63], v[152:155], v[186:189], v[60:63]
	v_mfma_f32_16x16x32_bf16 v[60:63], v[156:159], v[190:193], v[60:63]
	v_mfma_f32_16x16x32_bf16 v[56:59], v[160:163], v[186:189], v[56:59]
	v_mfma_f32_16x16x32_bf16 v[56:59], v[164:167], v[190:193], v[56:59]
	v_mfma_f32_16x16x32_bf16 v[40:43], v[160:163], v[194:197], v[40:43]
	v_mfma_f32_16x16x32_bf16 v[40:43], v[164:167], v[198:201], v[40:43]
	v_mfma_f32_16x16x32_bf16 v[44:47], v[152:155], v[194:197], v[44:47]
	v_mfma_f32_16x16x32_bf16 v[44:47], v[156:159], v[198:201], v[44:47]
	v_mfma_f32_16x16x32_bf16 v[28:31], v[152:155], v[202:205], v[28:31]
	v_mfma_f32_16x16x32_bf16 v[28:31], v[156:159], v[206:209], v[28:31]
	v_mfma_f32_16x16x32_bf16 v[24:27], v[160:163], v[202:205], v[24:27]
	v_mfma_f32_16x16x32_bf16 v[24:27], v[164:167], v[206:209], v[24:27]
	v_mfma_f32_16x16x32_bf16 v[8:11], v[160:163], v[210:213], v[8:11]
	v_mfma_f32_16x16x32_bf16 v[8:11], v[164:167], v[214:217], v[8:11]
	v_mfma_f32_16x16x32_bf16 v[12:15], v[152:155], v[210:213], v[12:15]
	v_mfma_f32_16x16x32_bf16 v[12:15], v[156:159], v[214:217], v[12:15]
	v_mfma_f32_16x16x32_bf16 v[52:55], v[168:171], v[186:189], v[52:55]
	v_mfma_f32_16x16x32_bf16 v[52:55], v[174:177], v[190:193], v[52:55]
	v_mfma_f32_16x16x32_bf16 v[48:51], v[178:181], v[186:189], v[48:51]
	v_mfma_f32_16x16x32_bf16 v[48:51], v[182:185], v[190:193], v[48:51]
	v_mfma_f32_16x16x32_bf16 v[32:35], v[178:181], v[194:197], v[32:35]
	v_mfma_f32_16x16x32_bf16 v[32:35], v[182:185], v[198:201], v[32:35]
	v_mfma_f32_16x16x32_bf16 v[36:39], v[168:171], v[194:197], v[36:39]
	v_mfma_f32_16x16x32_bf16 v[36:39], v[174:177], v[198:201], v[36:39]
	v_mfma_f32_16x16x32_bf16 v[20:23], v[168:171], v[202:205], v[20:23]
	v_mfma_f32_16x16x32_bf16 v[20:23], v[174:177], v[206:209], v[20:23]
	v_mfma_f32_16x16x32_bf16 v[16:19], v[178:181], v[202:205], v[16:19]
	v_mfma_f32_16x16x32_bf16 v[16:19], v[182:185], v[206:209], v[16:19]
	v_mfma_f32_16x16x32_bf16 v[0:3], v[178:181], v[210:213], v[0:3]
	v_mfma_f32_16x16x32_bf16 v[0:3], v[182:185], v[214:217], v[0:3]
	v_mfma_f32_16x16x32_bf16 v[4:7], v[168:171], v[210:213], v[4:7]
	v_mfma_f32_16x16x32_bf16 v[4:7], v[174:177], v[214:217], v[4:7]
	s_barrier
	s_add_i32 s48, 0, 0x18000
	s_add_i32 s49, 0, 0x1c000
	v_add_u32_e32 v164, s48, v129
	v_add_u32_e32 v173, s49, v129
	ds_read_b128 v[152:155], v164
	ds_read_b128 v[156:159], v164 offset:1024
	ds_read_b128 v[160:163], v164 offset:2048
	ds_read_b128 v[164:167], v164 offset:3072
	ds_read_b128 v[168:171], v173
	ds_read_b128 v[174:177], v173 offset:1024
	ds_read_b128 v[178:181], v173 offset:2048
	ds_read_b128 v[182:185], v173 offset:3072
	s_add_u32 s24, s24, 0x160000
	s_addc_u32 s25, s25, 0
	s_mov_b32 m0, s35
	ds_read_b128 v[186:189], v151 offset:32768
	ds_read_b128 v[190:193], v151 offset:33792
	ds_read_b128 v[194:197], v151 offset:34816
	ds_read_b128 v[198:201], v151 offset:35840
	ds_read_b128 v[202:205], v151 offset:36864
	ds_read_b128 v[206:209], v151 offset:37888
	ds_read_b128 v[210:213], v151 offset:38912
	ds_read_b128 v[214:217], v151 offset:39936
	global_load_lds_dwordx4 v130, s[24:25]
	s_mov_b32 m0, s36
	s_nop 0
	global_load_lds_dwordx4 v134, s[24:25]
	s_waitcnt vmcnt(8)
	s_waitcnt lgkmcnt(0)
	s_barrier
	s_waitcnt lgkmcnt(0)
	v_mfma_f32_16x16x32_bf16 v[124:127], v[152:155], v[186:189], v[124:127]
	v_mfma_f32_16x16x32_bf16 v[124:127], v[156:159], v[190:193], v[124:127]
	v_mfma_f32_16x16x32_bf16 v[120:123], v[160:163], v[186:189], v[120:123]
	v_mfma_f32_16x16x32_bf16 v[120:123], v[164:167], v[190:193], v[120:123]
	v_mfma_f32_16x16x32_bf16 v[104:107], v[160:163], v[194:197], v[104:107]
	v_mfma_f32_16x16x32_bf16 v[104:107], v[164:167], v[198:201], v[104:107]
	v_mfma_f32_16x16x32_bf16 v[108:111], v[152:155], v[194:197], v[108:111]
	v_mfma_f32_16x16x32_bf16 v[108:111], v[156:159], v[198:201], v[108:111]
	v_mfma_f32_16x16x32_bf16 v[92:95], v[152:155], v[202:205], v[92:95]
	v_mfma_f32_16x16x32_bf16 v[92:95], v[156:159], v[206:209], v[92:95]
	v_mfma_f32_16x16x32_bf16 v[88:91], v[160:163], v[202:205], v[88:91]
	v_mfma_f32_16x16x32_bf16 v[88:91], v[164:167], v[206:209], v[88:91]
	v_mfma_f32_16x16x32_bf16 v[72:75], v[160:163], v[210:213], v[72:75]
	v_mfma_f32_16x16x32_bf16 v[72:75], v[164:167], v[214:217], v[72:75]
	v_mfma_f32_16x16x32_bf16 v[76:79], v[152:155], v[210:213], v[76:79]
	v_mfma_f32_16x16x32_bf16 v[76:79], v[156:159], v[214:217], v[76:79]
	v_mfma_f32_16x16x32_bf16 v[116:119], v[168:171], v[186:189], v[116:119]
	v_mfma_f32_16x16x32_bf16 v[116:119], v[174:177], v[190:193], v[116:119]
	v_mfma_f32_16x16x32_bf16 v[112:115], v[178:181], v[186:189], v[112:115]
	v_mfma_f32_16x16x32_bf16 v[112:115], v[182:185], v[190:193], v[112:115]
	v_mfma_f32_16x16x32_bf16 v[96:99], v[178:181], v[194:197], v[96:99]
	v_mfma_f32_16x16x32_bf16 v[96:99], v[182:185], v[198:201], v[96:99]
	v_mfma_f32_16x16x32_bf16 v[100:103], v[168:171], v[194:197], v[100:103]
	v_mfma_f32_16x16x32_bf16 v[100:103], v[174:177], v[198:201], v[100:103]
	v_mfma_f32_16x16x32_bf16 v[84:87], v[168:171], v[202:205], v[84:87]
	v_mfma_f32_16x16x32_bf16 v[84:87], v[174:177], v[206:209], v[84:87]
	v_mfma_f32_16x16x32_bf16 v[80:83], v[178:181], v[202:205], v[80:83]
	v_mfma_f32_16x16x32_bf16 v[80:83], v[182:185], v[206:209], v[80:83]
	v_mfma_f32_16x16x32_bf16 v[64:67], v[178:181], v[210:213], v[64:67]
	v_mfma_f32_16x16x32_bf16 v[64:67], v[182:185], v[214:217], v[64:67]
	v_mfma_f32_16x16x32_bf16 v[68:71], v[168:171], v[210:213], v[68:71]
	v_mfma_f32_16x16x32_bf16 v[68:71], v[174:177], v[214:217], v[68:71]
	s_barrier
	s_add_i32 s24, s48, s31
	s_add_u32 s98, s22, 0x80
	s_addc_u32 s99, s23, 0
	s_mov_b32 m0, s24
	ds_read_b128 v[186:189], v151 offset:49152
	ds_read_b128 v[190:193], v151 offset:50176
	ds_read_b128 v[194:197], v151 offset:51200
	ds_read_b128 v[198:201], v151 offset:52224
	ds_read_b128 v[202:205], v151 offset:53248
	ds_read_b128 v[206:209], v151 offset:54272
	ds_read_b128 v[210:213], v151 offset:55296
	ds_read_b128 v[214:217], v151 offset:56320
	global_load_lds_dwordx4 v132, s[98:99]
	s_add_i32 m0, s24, 0x2000
	s_add_u32 s22, s22, 0x160080
	s_addc_u32 s23, s23, 0
	s_add_i32 s24, s49, s31
	global_load_lds_dwordx4 v136, s[98:99]
	s_mov_b32 m0, s24
	s_nop 0
	global_load_lds_dwordx4 v132, s[22:23]
	s_add_i32 m0, s24, 0x2000
	s_nop 0
	global_load_lds_dwordx4 v136, s[22:23]
	s_mov_b32 m0, s37
	s_nop 0
	global_load_lds_dwordx4 v130, s[100:101]
	s_mov_b32 m0, s38
	s_nop 0
	global_load_lds_dwordx4 v134, s[100:101]
	s_waitcnt vmcnt(8)
	s_waitcnt lgkmcnt(0)
	s_barrier
	s_waitcnt lgkmcnt(0)
	v_mfma_f32_16x16x32_bf16 v[60:63], v[152:155], v[186:189], v[60:63]
	v_mfma_f32_16x16x32_bf16 v[60:63], v[156:159], v[190:193], v[60:63]
	v_mfma_f32_16x16x32_bf16 v[56:59], v[160:163], v[186:189], v[56:59]
	v_mfma_f32_16x16x32_bf16 v[56:59], v[164:167], v[190:193], v[56:59]
	v_mfma_f32_16x16x32_bf16 v[40:43], v[160:163], v[194:197], v[40:43]
	v_mfma_f32_16x16x32_bf16 v[40:43], v[164:167], v[198:201], v[40:43]
	v_mfma_f32_16x16x32_bf16 v[44:47], v[152:155], v[194:197], v[44:47]
	v_mfma_f32_16x16x32_bf16 v[44:47], v[156:159], v[198:201], v[44:47]
	v_mfma_f32_16x16x32_bf16 v[28:31], v[152:155], v[202:205], v[28:31]
	v_mfma_f32_16x16x32_bf16 v[28:31], v[156:159], v[206:209], v[28:31]
	v_mfma_f32_16x16x32_bf16 v[24:27], v[160:163], v[202:205], v[24:27]
	v_mfma_f32_16x16x32_bf16 v[24:27], v[164:167], v[206:209], v[24:27]
	v_mfma_f32_16x16x32_bf16 v[8:11], v[160:163], v[210:213], v[8:11]
	v_mfma_f32_16x16x32_bf16 v[8:11], v[164:167], v[214:217], v[8:11]
	v_mfma_f32_16x16x32_bf16 v[12:15], v[152:155], v[210:213], v[12:15]
	v_mfma_f32_16x16x32_bf16 v[12:15], v[156:159], v[214:217], v[12:15]
	v_mfma_f32_16x16x32_bf16 v[52:55], v[168:171], v[186:189], v[52:55]
	v_mfma_f32_16x16x32_bf16 v[52:55], v[174:177], v[190:193], v[52:55]
	v_mfma_f32_16x16x32_bf16 v[48:51], v[178:181], v[186:189], v[48:51]
	v_mfma_f32_16x16x32_bf16 v[48:51], v[182:185], v[190:193], v[48:51]
	v_mfma_f32_16x16x32_bf16 v[32:35], v[178:181], v[194:197], v[32:35]
	v_mfma_f32_16x16x32_bf16 v[32:35], v[182:185], v[198:201], v[32:35]
	v_mfma_f32_16x16x32_bf16 v[36:39], v[168:171], v[194:197], v[36:39]
	v_mfma_f32_16x16x32_bf16 v[36:39], v[174:177], v[198:201], v[36:39]
	v_mfma_f32_16x16x32_bf16 v[20:23], v[168:171], v[202:205], v[20:23]
	v_mfma_f32_16x16x32_bf16 v[20:23], v[174:177], v[206:209], v[20:23]
	v_mfma_f32_16x16x32_bf16 v[16:19], v[178:181], v[202:205], v[16:19]
	v_mfma_f32_16x16x32_bf16 v[16:19], v[182:185], v[206:209], v[16:19]
	v_mfma_f32_16x16x32_bf16 v[0:3], v[178:181], v[210:213], v[0:3]
	v_mfma_f32_16x16x32_bf16 v[0:3], v[182:185], v[214:217], v[0:3]
	v_mfma_f32_16x16x32_bf16 v[4:7], v[168:171], v[210:213], v[4:7]
	v_mfma_f32_16x16x32_bf16 v[4:7], v[174:177], v[214:217], v[4:7]
	s_barrier
	s_add_i32 s47, s47, 2
	s_add_u32 s20, s20, 0x100
	s_addc_u32 s21, s21, 0
	s_cmpk_gt_u32 s47, 0x55
	s_cbranch_scc0 .LBB0_849
	s_add_u32 s20, s45, 0xffffff00
	s_addc_u32 s21, s46, -1
	s_and_b64 vcc, exec, s[4:5]
	s_cbranch_vccnz .LBB0_852
	v_mov_b32_e32 v0, 0
	s_mov_b32 s12, s42
	s_mov_b32 s13, s43
	s_mov_b64 s[14:15], s[18:19]
	s_mov_b32 s39, s44
	v_mov_b32_e32 v1, v0
	v_mov_b32_e32 v2, v0
	v_mov_b32_e32 v3, v0
	v_mov_b32_e32 v4, v0
	v_mov_b32_e32 v5, v0
	v_mov_b32_e32 v6, v0
	v_mov_b32_e32 v7, v0
	v_mov_b32_e32 v16, v0
	v_mov_b32_e32 v17, v0
	v_mov_b32_e32 v18, v0
	v_mov_b32_e32 v19, v0
	v_mov_b32_e32 v20, v0
	v_mov_b32_e32 v21, v0
	v_mov_b32_e32 v22, v0
	v_mov_b32_e32 v23, v0
	v_mov_b32_e32 v32, v0
	v_mov_b32_e32 v33, v0
	v_mov_b32_e32 v34, v0
	v_mov_b32_e32 v35, v0
	v_mov_b32_e32 v36, v0
	v_mov_b32_e32 v37, v0
	v_mov_b32_e32 v38, v0
	v_mov_b32_e32 v39, v0
	v_mov_b32_e32 v48, v0
	v_mov_b32_e32 v49, v0
	v_mov_b32_e32 v50, v0
	v_mov_b32_e32 v51, v0
	v_mov_b32_e32 v52, v0
	v_mov_b32_e32 v53, v0
	v_mov_b32_e32 v54, v0
	v_mov_b32_e32 v55, v0
	v_mov_b32_e32 v8, v0
	v_mov_b32_e32 v9, v0
	v_mov_b32_e32 v10, v0
	v_mov_b32_e32 v11, v0
	v_mov_b32_e32 v12, v0
	v_mov_b32_e32 v13, v0
	v_mov_b32_e32 v14, v0
	v_mov_b32_e32 v15, v0
	v_mov_b32_e32 v24, v0
	v_mov_b32_e32 v25, v0
	v_mov_b32_e32 v26, v0
	v_mov_b32_e32 v27, v0
	v_mov_b32_e32 v28, v0
	v_mov_b32_e32 v29, v0
	v_mov_b32_e32 v30, v0
	v_mov_b32_e32 v31, v0
	v_mov_b32_e32 v40, v0
	v_mov_b32_e32 v41, v0
	v_mov_b32_e32 v42, v0
	v_mov_b32_e32 v43, v0
	v_mov_b32_e32 v44, v0
	v_mov_b32_e32 v45, v0
	v_mov_b32_e32 v46, v0
	v_mov_b32_e32 v47, v0
	v_mov_b32_e32 v56, v0
	v_mov_b32_e32 v57, v0
	v_mov_b32_e32 v58, v0
	v_mov_b32_e32 v59, v0
	v_mov_b32_e32 v60, v0
	v_mov_b32_e32 v61, v0
	v_mov_b32_e32 v62, v0
	v_mov_b32_e32 v63, v0
	v_mov_b32_e32 v64, v0
	v_mov_b32_e32 v65, v0
	v_mov_b32_e32 v66, v0
	v_mov_b32_e32 v67, v0
	v_mov_b32_e32 v68, v0
	v_mov_b32_e32 v69, v0
	v_mov_b32_e32 v70, v0
	v_mov_b32_e32 v71, v0
	v_mov_b32_e32 v80, v0
	v_mov_b32_e32 v81, v0
	v_mov_b32_e32 v82, v0
	v_mov_b32_e32 v83, v0
	v_mov_b32_e32 v84, v0
	v_mov_b32_e32 v85, v0
	v_mov_b32_e32 v86, v0
	v_mov_b32_e32 v87, v0
	v_mov_b32_e32 v96, v0
	v_mov_b32_e32 v97, v0
	v_mov_b32_e32 v98, v0
	v_mov_b32_e32 v99, v0
	v_mov_b32_e32 v100, v0
	v_mov_b32_e32 v101, v0
	v_mov_b32_e32 v102, v0
	v_mov_b32_e32 v103, v0
	v_mov_b32_e32 v112, v0
	v_mov_b32_e32 v113, v0
	v_mov_b32_e32 v114, v0
	v_mov_b32_e32 v115, v0
	v_mov_b32_e32 v116, v0
	v_mov_b32_e32 v117, v0
	v_mov_b32_e32 v118, v0
	v_mov_b32_e32 v119, v0
	v_mov_b32_e32 v72, v0
	v_mov_b32_e32 v73, v0
	v_mov_b32_e32 v74, v0
	v_mov_b32_e32 v75, v0
	v_mov_b32_e32 v76, v0
	v_mov_b32_e32 v77, v0
	v_mov_b32_e32 v78, v0
	v_mov_b32_e32 v79, v0
	v_mov_b32_e32 v88, v0
	v_mov_b32_e32 v89, v0
	v_mov_b32_e32 v90, v0
	v_mov_b32_e32 v91, v0
	v_mov_b32_e32 v92, v0
	v_mov_b32_e32 v93, v0
	v_mov_b32_e32 v94, v0
	v_mov_b32_e32 v95, v0
	v_mov_b32_e32 v104, v0
	v_mov_b32_e32 v105, v0
	v_mov_b32_e32 v106, v0
	v_mov_b32_e32 v107, v0
	v_mov_b32_e32 v108, v0
	v_mov_b32_e32 v109, v0
	v_mov_b32_e32 v110, v0
	v_mov_b32_e32 v111, v0
	v_mov_b32_e32 v120, v0
	v_mov_b32_e32 v121, v0
	v_mov_b32_e32 v122, v0
	v_mov_b32_e32 v123, v0
	v_mov_b32_e32 v124, v0
	v_mov_b32_e32 v125, v0
	v_mov_b32_e32 v126, v0
	v_mov_b32_e32 v127, v0
	s_andn2_b64 vcc, exec, s[0:1]
	s_cbranch_vccnz .LBB0_853
	s_branch .LBB0_854

	.amdhsa_kernel _Z9hymba_fwd4Args
		.amdhsa_group_segment_fixed_size 0
		.amdhsa_private_segment_fixed_size 0
		.amdhsa_kernarg_size 416
		.amdhsa_user_sgpr_count 2
		.amdhsa_user_sgpr_dispatch_ptr 0
		.amdhsa_user_sgpr_queue_ptr 0
		.amdhsa_user_sgpr_kernarg_segment_ptr 1
		.amdhsa_user_sgpr_dispatch_id 0
		.amdhsa_user_sgpr_kernarg_preload_length 0
		.amdhsa_user_sgpr_kernarg_preload_offset 0
		.amdhsa_user_sgpr_private_segment_size 0
		.amdhsa_uses_dynamic_stack 0
		.amdhsa_enable_private_segment 0
		.amdhsa_system_sgpr_workgroup_id_x 1
		.amdhsa_system_sgpr_workgroup_id_y 0
		.amdhsa_system_sgpr_workgroup_id_z 0
		.amdhsa_system_sgpr_workgroup_info 0
		.amdhsa_system_vgpr_workitem_id 2
		.amdhsa_next_free_vgpr 252
		.amdhsa_next_free_sgpr 102
		.amdhsa_accum_offset 252
		.amdhsa_reserve_vcc 1
		.amdhsa_float_round_mode_32 0
		.amdhsa_float_round_mode_16_64 0
		.amdhsa_float_denorm_mode_32 3
		.amdhsa_float_denorm_mode_16_64 3
		.amdhsa_dx10_clamp 1
		.amdhsa_ieee_mode 1
		.amdhsa_fp16_overflow 0
		.amdhsa_tg_split 0
		.amdhsa_exception_fp_ieee_invalid_op 0
		.amdhsa_exception_fp_denorm_src 0
		.amdhsa_exception_fp_ieee_div_zero 0
		.amdhsa_exception_fp_ieee_overflow 0
		.amdhsa_exception_fp_ieee_underflow 0
		.amdhsa_exception_fp_ieee_inexact 0
		.amdhsa_exception_int_div_zero 0
	.end_amdhsa_kernel

amdhsa.kernels:
  - .agpr_count:     0
    .args:
      - .offset:         0
        .size:           160
        .value_kind:     by_value
      - .offset:         160
        .size:           4
        .value_kind:     hidden_block_count_x
      - .offset:         164
        .size:           4
        .value_kind:     hidden_block_count_y
      - .offset:         168
        .size:           4
        .value_kind:     hidden_block_count_z
      - .offset:         172
        .size:           2
        .value_kind:     hidden_group_size_x
      - .offset:         174
        .size:           2
        .value_kind:     hidden_group_size_y
      - .offset:         176
        .size:           2
        .value_kind:     hidden_group_size_z
      - .offset:         178
        .size:           2
        .value_kind:     hidden_remainder_x
      - .offset:         180
        .size:           2
        .value_kind:     hidden_remainder_y
      - .offset:         182
        .size:           2
        .value_kind:     hidden_remainder_z
      - .offset:         200
        .size:           8
        .value_kind:     hidden_global_offset_x
      - .offset:         208
        .size:           8
        .value_kind:     hidden_global_offset_y
      - .offset:         216
        .size:           8
        .value_kind:     hidden_global_offset_z
      - .offset:         224
        .size:           2
        .value_kind:     hidden_grid_dims
      - .offset:         248
        .size:           8
        .value_kind:     hidden_multigrid_sync_arg
      - .offset:         280
        .size:           4
        .value_kind:     hidden_dynamic_lds_size
    .group_segment_fixed_size: 0
    .kernarg_segment_align: 8
    .kernarg_segment_size: 416
    .language:       OpenCL C
    .language_version:
      - 2
      - 0
    .max_flat_workgroup_size: 512
    .name:           _Z9hymba_fwd4Args
    .private_segment_fixed_size: 0
    .sgpr_count:     108
    .sgpr_spill_count: 83
    .symbol:         _Z9hymba_fwd4Args.kd
    .uniform_work_group_size: 1
    .uses_dynamic_stack: false
    .vgpr_count:     252
    .vgpr_spill_count: 0
    .wavefront_size: 64
